# AQKV output stores (q/k rows and V^T) marked non-temporal
# baseline (speedup 1.0000x reference)
.LBB0_1261:
	ds_read2_b32 v[140:141], v219 offset1:32
	ds_read2_b32 v[136:137], v219 offset0:64 offset1:96
	v_and_b32_e32 v0, 1, v199
	v_and_b32_e32 v228, 63, v198
	v_mov_b32_e32 v142, v199
	v_mov_b32_e32 v139, v202
	v_mov_b32_e32 v130, v200
	v_bfe_u32 v131, v199, 1, 1
	v_mov_b32_e32 v135, v201
	s_lshl_b32 s1, s6, 8
	v_readfirstlane_b32 s0, v131
	s_lshl_b32 s3, s0, 7
	s_add_i32 s3, s3, s1
	v_lshl_add_u32 v134, v130, 7, s2
	v_lshlrev_b32_e32 v0, 6, v0
	v_lshlrev_b32_e32 v130, 2, v139
	v_add_u32_e32 v138, s3, v0
	s_mov_b64 s[0:1], -1
	s_cmpk_gt_i32 s3, 0x7ff
	v_ashrrev_i32_e32 v131, 31, v130
	s_cbranch_scc0 .LBB0_1263
	v_readfirstlane_b32 s8, v204
	s_lshr_b32 s8, s8, 6
	s_and_b32 s9, s8, 1
	s_lshr_b32 s10, s8, 2
	s_lshl_b32 s11, s9, 6
	s_add_i32 s11, s11, s3
	s_sub_i32 s11, s11, 0x800
	s_lshr_b32 s12, s11, 7
	s_and_b32 s11, s11, 0x7f
	s_lshl_b32 s10, s10, 7
	s_add_i32 s10, s10, s2
	s_lshr_b32 s13, s10, 12
	s_and_b32 s10, s10, 0xfff
	s_lshl_b32 s13, s13, 3
	s_add_i32 s13, s13, s12
	s_lshl_b32 s13, s13, 7
	s_add_i32 s13, s13, s11
	s_lshl_b32 s13, s13, 13
	s_lshl_b32 s10, s10, 1
	s_add_u32 s13, s13, s10
	v_readlane_b32 s14, v252, 27
	v_readlane_b32 s15, v252, 28
	s_add_u32 s14, s14, s13
	s_addc_u32 s15, s15, 0
	v_and_b32_e32 v130, 63, v204
	v_and_b32_e32 v131, 31, v130
	v_lshrrev_b32_e32 v132, 5, v130
	s_lshl_b32 s8, s8, 14
	v_lshlrev_b32_e32 v133, 10, v132
	v_lshl_add_u32 v133, v131, 1, v133
	v_add_u32_e32 v133, s8, v133
	v_lshrrev_b32_e32 v134, 4, v130
	v_and_b32_e32 v135, 15, v130
	v_lshlrev_b32_e32 v135, 4, v135
	v_lshl_add_u32 v138, v134, 8, v135
	v_add_u32_e32 v138, s8, v138
	v_lshl_add_u32 v139, v134, 13, v135
	s_waitcnt lgkmcnt(0)
	v_mul_f32_e32 v142, v98, v140
	v_mul_f32_e32 v143, v99, v140
	v_cvt_pk_bf16_f32 v142, v142, v143
	ds_write_b16 v133, v142 offset:0
	ds_write_b16_d16_hi v133, v142 offset:256
	v_mul_f32_e32 v144, v100, v140
	v_mul_f32_e32 v145, v101, v140
	v_cvt_pk_bf16_f32 v144, v144, v145
	ds_write_b16 v133, v144 offset:512
	ds_write_b16_d16_hi v133, v144 offset:768
	v_mul_f32_e32 v146, v102, v140
	v_mul_f32_e32 v147, v103, v140
	v_cvt_pk_bf16_f32 v146, v146, v147
	ds_write_b16 v133, v146 offset:2048
	ds_write_b16_d16_hi v133, v146 offset:2304
	v_mul_f32_e32 v148, v104, v140
	v_mul_f32_e32 v149, v105, v140
	v_cvt_pk_bf16_f32 v148, v148, v149
	ds_write_b16 v133, v148 offset:2560
	ds_write_b16_d16_hi v133, v148 offset:2816
	v_mul_f32_e32 v142, v106, v140
	v_mul_f32_e32 v143, v107, v140
	v_cvt_pk_bf16_f32 v142, v142, v143
	ds_write_b16 v133, v142 offset:4096
	ds_write_b16_d16_hi v133, v142 offset:4352
	v_mul_f32_e32 v144, v108, v140
	v_mul_f32_e32 v145, v109, v140
	v_cvt_pk_bf16_f32 v144, v144, v145
	ds_write_b16 v133, v144 offset:4608
	ds_write_b16_d16_hi v133, v144 offset:4864
	v_mul_f32_e32 v146, v110, v140
	v_mul_f32_e32 v147, v111, v140
	v_cvt_pk_bf16_f32 v146, v146, v147
	ds_write_b16 v133, v146 offset:6144
	ds_write_b16_d16_hi v133, v146 offset:6400
	v_mul_f32_e32 v148, v112, v140
	v_mul_f32_e32 v149, v113, v140
	v_cvt_pk_bf16_f32 v148, v148, v149
	ds_write_b16 v133, v148 offset:6656
	ds_write_b16_d16_hi v133, v148 offset:6912
	v_mul_f32_e32 v142, v114, v140
	v_mul_f32_e32 v143, v115, v140
	v_cvt_pk_bf16_f32 v142, v142, v143
	ds_write_b16 v133, v142 offset:8192
	ds_write_b16_d16_hi v133, v142 offset:8448
	v_mul_f32_e32 v144, v116, v140
	v_mul_f32_e32 v145, v117, v140
	v_cvt_pk_bf16_f32 v144, v144, v145
	ds_write_b16 v133, v144 offset:8704
	ds_write_b16_d16_hi v133, v144 offset:8960
	v_mul_f32_e32 v146, v118, v140
	v_mul_f32_e32 v147, v119, v140
	v_cvt_pk_bf16_f32 v146, v146, v147
	ds_write_b16 v133, v146 offset:10240
	ds_write_b16_d16_hi v133, v146 offset:10496
	v_mul_f32_e32 v148, v120, v140
	v_mul_f32_e32 v149, v121, v140
	v_cvt_pk_bf16_f32 v148, v148, v149
	ds_write_b16 v133, v148 offset:10752
	ds_write_b16_d16_hi v133, v148 offset:11008
	v_mul_f32_e32 v142, v122, v140
	v_mul_f32_e32 v143, v123, v140
	v_cvt_pk_bf16_f32 v142, v142, v143
	ds_write_b16 v133, v142 offset:12288
	ds_write_b16_d16_hi v133, v142 offset:12544
	v_mul_f32_e32 v144, v124, v140
	v_mul_f32_e32 v145, v125, v140
	v_cvt_pk_bf16_f32 v144, v144, v145
	ds_write_b16 v133, v144 offset:12800
	ds_write_b16_d16_hi v133, v144 offset:13056
	v_mul_f32_e32 v146, v126, v140
	v_mul_f32_e32 v147, v127, v140
	v_cvt_pk_bf16_f32 v146, v146, v147
	ds_write_b16 v133, v146 offset:14336
	ds_write_b16_d16_hi v133, v146 offset:14592
	v_mul_f32_e32 v148, v128, v140
	v_mul_f32_e32 v149, v129, v140
	v_cvt_pk_bf16_f32 v148, v148, v149
	ds_write_b16 v133, v148 offset:14848
	ds_write_b16_d16_hi v133, v148 offset:15104
	v_mul_f32_e32 v142, v82, v141
	v_mul_f32_e32 v143, v83, v141
	v_cvt_pk_bf16_f32 v142, v142, v143
	ds_write_b16 v133, v142 offset:64
	ds_write_b16_d16_hi v133, v142 offset:320
	v_mul_f32_e32 v144, v84, v141
	v_mul_f32_e32 v145, v85, v141
	v_cvt_pk_bf16_f32 v144, v144, v145
	ds_write_b16 v133, v144 offset:576
	ds_write_b16_d16_hi v133, v144 offset:832
	v_mul_f32_e32 v146, v86, v141
	v_mul_f32_e32 v147, v87, v141
	v_cvt_pk_bf16_f32 v146, v146, v147
	ds_write_b16 v133, v146 offset:2112
	ds_write_b16_d16_hi v133, v146 offset:2368
	v_mul_f32_e32 v148, v88, v141
	v_mul_f32_e32 v149, v89, v141
	v_cvt_pk_bf16_f32 v148, v148, v149
	ds_write_b16 v133, v148 offset:2624
	ds_write_b16_d16_hi v133, v148 offset:2880
	v_mul_f32_e32 v142, v90, v141
	v_mul_f32_e32 v143, v91, v141
	v_cvt_pk_bf16_f32 v142, v142, v143
	ds_write_b16 v133, v142 offset:4160
	ds_write_b16_d16_hi v133, v142 offset:4416
	v_mul_f32_e32 v144, v92, v141
	v_mul_f32_e32 v145, v93, v141
	v_cvt_pk_bf16_f32 v144, v144, v145
	ds_write_b16 v133, v144 offset:4672
	ds_write_b16_d16_hi v133, v144 offset:4928
	v_mul_f32_e32 v146, v94, v141
	v_mul_f32_e32 v147, v95, v141
	v_cvt_pk_bf16_f32 v146, v146, v147
	ds_write_b16 v133, v146 offset:6208
	ds_write_b16_d16_hi v133, v146 offset:6464
	v_mul_f32_e32 v148, v96, v141
	v_mul_f32_e32 v149, v97, v141
	v_cvt_pk_bf16_f32 v148, v148, v149
	ds_write_b16 v133, v148 offset:6720
	ds_write_b16_d16_hi v133, v148 offset:6976
	v_mul_f32_e32 v142, v66, v141
	v_mul_f32_e32 v143, v67, v141
	v_cvt_pk_bf16_f32 v142, v142, v143
	ds_write_b16 v133, v142 offset:8256
	ds_write_b16_d16_hi v133, v142 offset:8512
	v_mul_f32_e32 v144, v68, v141
	v_mul_f32_e32 v145, v69, v141
	v_cvt_pk_bf16_f32 v144, v144, v145
	ds_write_b16 v133, v144 offset:8768
	ds_write_b16_d16_hi v133, v144 offset:9024
	v_mul_f32_e32 v146, v70, v141
	v_mul_f32_e32 v147, v71, v141
	v_cvt_pk_bf16_f32 v146, v146, v147
	ds_write_b16 v133, v146 offset:10304
	ds_write_b16_d16_hi v133, v146 offset:10560
	v_mul_f32_e32 v148, v72, v141
	v_mul_f32_e32 v149, v73, v141
	v_cvt_pk_bf16_f32 v148, v148, v149
	ds_write_b16 v133, v148 offset:10816
	ds_write_b16_d16_hi v133, v148 offset:11072
	v_mul_f32_e32 v142, v74, v141
	v_mul_f32_e32 v143, v75, v141
	v_cvt_pk_bf16_f32 v142, v142, v143
	ds_write_b16 v133, v142 offset:12352
	ds_write_b16_d16_hi v133, v142 offset:12608
	v_mul_f32_e32 v144, v76, v141
	v_mul_f32_e32 v145, v77, v141
	v_cvt_pk_bf16_f32 v144, v144, v145
	ds_write_b16 v133, v144 offset:12864
	ds_write_b16_d16_hi v133, v144 offset:13120
	v_mul_f32_e32 v146, v78, v141
	v_mul_f32_e32 v147, v79, v141
	v_cvt_pk_bf16_f32 v146, v146, v147
	ds_write_b16 v133, v146 offset:14400
	ds_write_b16_d16_hi v133, v146 offset:14656
	v_mul_f32_e32 v148, v80, v141
	v_mul_f32_e32 v149, v81, v141
	v_cvt_pk_bf16_f32 v148, v148, v149
	ds_write_b16 v133, v148 offset:14912
	ds_write_b16_d16_hi v133, v148 offset:15168
	v_mul_f32_e32 v142, v34, v136
	v_mul_f32_e32 v143, v35, v136
	v_cvt_pk_bf16_f32 v142, v142, v143
	ds_write_b16 v133, v142 offset:128
	ds_write_b16_d16_hi v133, v142 offset:384
	v_mul_f32_e32 v144, v36, v136
	v_mul_f32_e32 v145, v37, v136
	v_cvt_pk_bf16_f32 v144, v144, v145
	ds_write_b16 v133, v144 offset:640
	ds_write_b16_d16_hi v133, v144 offset:896
	v_mul_f32_e32 v146, v38, v136
	v_mul_f32_e32 v147, v39, v136
	v_cvt_pk_bf16_f32 v146, v146, v147
	ds_write_b16 v133, v146 offset:2176
	ds_write_b16_d16_hi v133, v146 offset:2432
	v_mul_f32_e32 v148, v40, v136
	v_mul_f32_e32 v149, v41, v136
	v_cvt_pk_bf16_f32 v148, v148, v149
	ds_write_b16 v133, v148 offset:2688
	ds_write_b16_d16_hi v133, v148 offset:2944
	v_mul_f32_e32 v142, v42, v136
	v_mul_f32_e32 v143, v43, v136
	v_cvt_pk_bf16_f32 v142, v142, v143
	ds_write_b16 v133, v142 offset:4224
	ds_write_b16_d16_hi v133, v142 offset:4480
	v_mul_f32_e32 v144, v44, v136
	v_mul_f32_e32 v145, v45, v136
	v_cvt_pk_bf16_f32 v144, v144, v145
	ds_write_b16 v133, v144 offset:4736
	ds_write_b16_d16_hi v133, v144 offset:4992
	v_mul_f32_e32 v146, v46, v136
	v_mul_f32_e32 v147, v47, v136
	v_cvt_pk_bf16_f32 v146, v146, v147
	ds_write_b16 v133, v146 offset:6272
	ds_write_b16_d16_hi v133, v146 offset:6528
	v_mul_f32_e32 v148, v48, v136
	v_mul_f32_e32 v149, v49, v136
	v_cvt_pk_bf16_f32 v148, v148, v149
	ds_write_b16 v133, v148 offset:6784
	ds_write_b16_d16_hi v133, v148 offset:7040
	v_mul_f32_e32 v142, v50, v136
	v_mul_f32_e32 v143, v51, v136
	v_cvt_pk_bf16_f32 v142, v142, v143
	ds_write_b16 v133, v142 offset:8320
	ds_write_b16_d16_hi v133, v142 offset:8576
	v_mul_f32_e32 v144, v52, v136
	v_mul_f32_e32 v145, v53, v136
	v_cvt_pk_bf16_f32 v144, v144, v145
	ds_write_b16 v133, v144 offset:8832
	ds_write_b16_d16_hi v133, v144 offset:9088
	v_mul_f32_e32 v146, v54, v136
	v_mul_f32_e32 v147, v55, v136
	v_cvt_pk_bf16_f32 v146, v146, v147
	ds_write_b16 v133, v146 offset:10368
	ds_write_b16_d16_hi v133, v146 offset:10624
	v_mul_f32_e32 v148, v56, v136
	v_mul_f32_e32 v149, v57, v136
	v_cvt_pk_bf16_f32 v148, v148, v149
	ds_write_b16 v133, v148 offset:10880
	ds_write_b16_d16_hi v133, v148 offset:11136
	v_mul_f32_e32 v142, v58, v136
	v_mul_f32_e32 v143, v59, v136
	v_cvt_pk_bf16_f32 v142, v142, v143
	ds_write_b16 v133, v142 offset:12416
	ds_write_b16_d16_hi v133, v142 offset:12672
	v_mul_f32_e32 v144, v60, v136
	v_mul_f32_e32 v145, v61, v136
	v_cvt_pk_bf16_f32 v144, v144, v145
	ds_write_b16 v133, v144 offset:12928
	ds_write_b16_d16_hi v133, v144 offset:13184
	v_mul_f32_e32 v146, v62, v136
	v_mul_f32_e32 v147, v63, v136
	v_cvt_pk_bf16_f32 v146, v146, v147
	ds_write_b16 v133, v146 offset:14464
	ds_write_b16_d16_hi v133, v146 offset:14720
	v_mul_f32_e32 v148, v64, v136
	v_mul_f32_e32 v149, v65, v136
	v_cvt_pk_bf16_f32 v148, v148, v149
	ds_write_b16 v133, v148 offset:14976
	ds_write_b16_d16_hi v133, v148 offset:15232
	v_mul_f32_e32 v142, v18, v137
	v_mul_f32_e32 v143, v19, v137
	v_cvt_pk_bf16_f32 v142, v142, v143
	ds_write_b16 v133, v142 offset:192
	ds_write_b16_d16_hi v133, v142 offset:448
	v_mul_f32_e32 v144, v20, v137
	v_mul_f32_e32 v145, v21, v137
	v_cvt_pk_bf16_f32 v144, v144, v145
	ds_write_b16 v133, v144 offset:704
	ds_write_b16_d16_hi v133, v144 offset:960
	v_mul_f32_e32 v146, v22, v137
	v_mul_f32_e32 v147, v23, v137
	v_cvt_pk_bf16_f32 v146, v146, v147
	ds_write_b16 v133, v146 offset:2240
	ds_write_b16_d16_hi v133, v146 offset:2496
	v_mul_f32_e32 v148, v24, v137
	v_mul_f32_e32 v149, v25, v137
	v_cvt_pk_bf16_f32 v148, v148, v149
	ds_write_b16 v133, v148 offset:2752
	ds_write_b16_d16_hi v133, v148 offset:3008
	v_mul_f32_e32 v142, v26, v137
	v_mul_f32_e32 v143, v27, v137
	v_cvt_pk_bf16_f32 v142, v142, v143
	ds_write_b16 v133, v142 offset:4288
	ds_write_b16_d16_hi v133, v142 offset:4544
	v_mul_f32_e32 v144, v28, v137
	v_mul_f32_e32 v145, v29, v137
	v_cvt_pk_bf16_f32 v144, v144, v145
	ds_write_b16 v133, v144 offset:4800
	ds_write_b16_d16_hi v133, v144 offset:5056
	v_mul_f32_e32 v146, v30, v137
	v_mul_f32_e32 v147, v31, v137
	v_cvt_pk_bf16_f32 v146, v146, v147
	ds_write_b16 v133, v146 offset:6336
	ds_write_b16_d16_hi v133, v146 offset:6592
	v_mul_f32_e32 v148, v32, v137
	v_mul_f32_e32 v149, v33, v137
	v_cvt_pk_bf16_f32 v148, v148, v149
	ds_write_b16 v133, v148 offset:6848
	ds_write_b16_d16_hi v133, v148 offset:7104
	v_mul_f32_e32 v142, v2, v137
	v_mul_f32_e32 v143, v3, v137
	v_cvt_pk_bf16_f32 v142, v142, v143
	ds_write_b16 v133, v142 offset:8384
	ds_write_b16_d16_hi v133, v142 offset:8640
	v_mul_f32_e32 v144, v4, v137
	v_mul_f32_e32 v145, v5, v137
	v_cvt_pk_bf16_f32 v144, v144, v145
	ds_write_b16 v133, v144 offset:8896
	ds_write_b16_d16_hi v133, v144 offset:9152
	v_mul_f32_e32 v146, v6, v137
	v_mul_f32_e32 v147, v7, v137
	v_cvt_pk_bf16_f32 v146, v146, v147
	ds_write_b16 v133, v146 offset:10432
	ds_write_b16_d16_hi v133, v146 offset:10688
	v_mul_f32_e32 v148, v8, v137
	v_mul_f32_e32 v149, v9, v137
	v_cvt_pk_bf16_f32 v148, v148, v149
	ds_write_b16 v133, v148 offset:10944
	ds_write_b16_d16_hi v133, v148 offset:11200
	v_mul_f32_e32 v142, v10, v137
	v_mul_f32_e32 v143, v11, v137
	v_cvt_pk_bf16_f32 v142, v142, v143
	ds_write_b16 v133, v142 offset:12480
	ds_write_b16_d16_hi v133, v142 offset:12736
	v_mul_f32_e32 v144, v12, v137
	v_mul_f32_e32 v145, v13, v137
	v_cvt_pk_bf16_f32 v144, v144, v145
	ds_write_b16 v133, v144 offset:12992
	ds_write_b16_d16_hi v133, v144 offset:13248
	v_mul_f32_e32 v146, v14, v137
	v_mul_f32_e32 v147, v15, v137
	v_cvt_pk_bf16_f32 v146, v146, v147
	ds_write_b16 v133, v146 offset:14528
	ds_write_b16_d16_hi v133, v146 offset:14784
	v_mul_f32_e32 v148, v16, v137
	v_mul_f32_e32 v149, v17, v137
	v_cvt_pk_bf16_f32 v148, v148, v149
	ds_write_b16 v133, v148 offset:15040
	ds_write_b16_d16_hi v133, v148 offset:15296
	s_waitcnt lgkmcnt(0)
	ds_read_b128 v[144:147], v138 offset:0
	ds_read_b128 v[148:151], v138 offset:1024
	ds_read_b128 v[152:155], v138 offset:2048
	ds_read_b128 v[156:159], v138 offset:3072
	s_waitcnt lgkmcnt(3)
	global_store_dwordx4 v139, v[144:147], s[14:15] nt
	s_waitcnt lgkmcnt(2)
	v_add_u32_e32 v161, 0x8000, v139
	global_store_dwordx4 v161, v[148:151], s[14:15] nt
	s_waitcnt lgkmcnt(1)
	v_add_u32_e32 v162, 0x10000, v139
	global_store_dwordx4 v162, v[152:155], s[14:15] nt
	s_waitcnt lgkmcnt(0)
	v_add_u32_e32 v163, 0x18000, v139
	global_store_dwordx4 v163, v[156:159], s[14:15] nt
	s_nop 1
	ds_read_b128 v[144:147], v138 offset:4096
	ds_read_b128 v[148:151], v138 offset:5120
	ds_read_b128 v[152:155], v138 offset:6144
	ds_read_b128 v[156:159], v138 offset:7168
	s_waitcnt lgkmcnt(3)
	v_add_u32_e32 v160, 0x20000, v139
	global_store_dwordx4 v160, v[144:147], s[14:15] nt
	s_waitcnt lgkmcnt(2)
	v_add_u32_e32 v161, 0x28000, v139
	global_store_dwordx4 v161, v[148:151], s[14:15] nt
	s_waitcnt lgkmcnt(1)
	v_add_u32_e32 v162, 0x30000, v139
	global_store_dwordx4 v162, v[152:155], s[14:15] nt
	s_waitcnt lgkmcnt(0)
	v_add_u32_e32 v163, 0x38000, v139
	global_store_dwordx4 v163, v[156:159], s[14:15] nt
	s_nop 1
	ds_read_b128 v[144:147], v138 offset:8192
	ds_read_b128 v[148:151], v138 offset:9216
	ds_read_b128 v[152:155], v138 offset:10240
	ds_read_b128 v[156:159], v138 offset:11264
	s_waitcnt lgkmcnt(3)
	v_add_u32_e32 v160, 0x40000, v139
	global_store_dwordx4 v160, v[144:147], s[14:15] nt
	s_waitcnt lgkmcnt(2)
	v_add_u32_e32 v161, 0x48000, v139
	global_store_dwordx4 v161, v[148:151], s[14:15] nt
	s_waitcnt lgkmcnt(1)
	v_add_u32_e32 v162, 0x50000, v139
	global_store_dwordx4 v162, v[152:155], s[14:15] nt
	s_waitcnt lgkmcnt(0)
	v_add_u32_e32 v163, 0x58000, v139
	global_store_dwordx4 v163, v[156:159], s[14:15] nt
	s_nop 1
	ds_read_b128 v[144:147], v138 offset:12288
	ds_read_b128 v[148:151], v138 offset:13312
	ds_read_b128 v[152:155], v138 offset:14336
	ds_read_b128 v[156:159], v138 offset:15360
	s_waitcnt lgkmcnt(3)
	v_add_u32_e32 v160, 0x60000, v139
	global_store_dwordx4 v160, v[144:147], s[14:15] nt
	s_waitcnt lgkmcnt(2)
	v_add_u32_e32 v161, 0x68000, v139
	global_store_dwordx4 v161, v[148:151], s[14:15] nt
	s_waitcnt lgkmcnt(1)
	v_add_u32_e32 v162, 0x70000, v139
	global_store_dwordx4 v162, v[152:155], s[14:15] nt
	s_waitcnt lgkmcnt(0)
	v_add_u32_e32 v163, 0x78000, v139
	global_store_dwordx4 v163, v[156:159], s[14:15] nt
	s_nop 1
	s_mov_b64 s[0:1], 0
.LBB0_1263:
	s_andn2_b64 vcc, exec, s[0:1]
	s_cbranch_vccnz .LBB0_1240
	v_readlane_b32 s36, v250, 19
	s_cmpk_lt_i32 s3, 0x400
	v_readlane_b32 s44, v250, 27
	v_readlane_b32 s45, v250, 28
	s_cselect_b64 vcc, -1, 0
	v_readlane_b32 s46, v250, 29
	v_readlane_b32 s47, v250, 30
	v_readlane_b32 s48, v250, 31
	v_readlane_b32 s49, v250, 32
	v_readlane_b32 s50, v250, 33
	v_readlane_b32 s51, v250, 34
	s_mov_b64 s[8:9], s[44:45]
	v_mov_b32_e32 v132, 0x3e38aa3b
	s_and_b64 s[0:1], vcc, exec
	s_mov_b64 s[10:11], s[46:47]
	v_and_b32_e32 v133, 64, v214
	v_cndmask_b32_e32 v237, 1.0, v132, vcc
	s_cselect_b32 s1, s9, s11
	s_cselect_b32 s0, s8, s10
	s_lshl_b32 s2, s20, 2
	v_xor_b32_e32 v132, 32, v214
	v_add_u32_e32 v133, 64, v133
	s_add_u32 s0, s0, s2
	v_cmp_lt_i32_e32 vcc, v132, v133
	s_addc_u32 s1, s1, 0
	v_lshlrev_b32_e32 v0, 14, v142
	v_cndmask_b32_e32 v132, v214, v132, vcc
	v_lshlrev_b32_e32 v239, 2, v132
	v_lshlrev_b32_e32 v132, 7, v135
	v_lshlrev_b32_e32 v133, 3, v139
	v_lshl_add_u64 v[158:159], v[130:131], 2, s[0:1]
	v_add3_u32 v215, v0, v132, v133
	v_ashrrev_i32_e32 v132, 3, v228
	s_waitcnt lgkmcnt(0)
	v_pk_mul_f32 v[160:161], v[126:127], v[140:141] op_sel_hi:[1,0]
	v_pk_mul_f32 v[162:163], v[128:129], v[140:141] op_sel_hi:[1,0]
	v_pk_mul_f32 v[164:165], v[100:101], v[140:141] op_sel_hi:[1,0]
	v_pk_mul_f32 v[170:171], v[98:99], v[140:141] op_sel_hi:[1,0]
	global_load_dwordx4 v[126:129], v[158:159], off
	global_load_dwordx4 v[98:101], v[158:159], off offset:32
	v_xor_b32_e32 v133, v132, v228
	v_lshlrev_b32_e32 v133, 4, v133
	v_add_u32_e32 v150, 32, v132
	v_and_or_b32 v0, v133, s55, v0
	v_ashrrev_i32_e32 v133, 31, v132
	v_ashrrev_i32_e32 v151, 31, v150
	v_lshl_add_u32 v229, v132, 7, v0
	v_lshlrev_b64 v[142:143], 12, v[132:133]
	v_add_u32_e32 v144, 8, v132
	v_add_u32_e32 v146, 16, v132
	v_add_u32_e32 v148, 24, v132
	v_lshl_add_u32 v233, v150, 7, v0
	v_lshlrev_b64 v[152:153], 12, v[150:151]
	v_add_u32_e32 v150, 40, v132
	v_add_u32_e32 v154, 48, v132
	v_add_u32_e32 v132, 56, v132
	v_ashrrev_i32_e32 v133, 31, v132
	v_lshl_add_u32 v236, v132, 7, v0
	v_lshlrev_b64 v[156:157], 12, v[132:133]
	v_pk_mul_f32 v[166:167], v[104:105], v[140:141] op_sel_hi:[1,0]
	v_pk_mul_f32 v[208:209], v[102:103], v[140:141] op_sel_hi:[1,0]
	global_load_dwordx4 v[130:133], v[158:159], off offset:64
	global_load_dwordx4 v[102:105], v[158:159], off offset:96
	v_pk_mul_f32 v[168:169], v[108:109], v[140:141] op_sel_hi:[1,0]
	v_pk_mul_f32 v[180:181], v[106:107], v[140:141] op_sel_hi:[1,0]
	v_pk_mul_f32 v[172:173], v[112:113], v[140:141] op_sel_hi:[1,0]
	v_pk_mul_f32 v[184:185], v[110:111], v[140:141] op_sel_hi:[1,0]
	global_load_dwordx4 v[110:113], v[158:159], off offset:128
	global_load_dwordx4 v[106:109], v[158:159], off offset:160
	v_pk_mul_f32 v[174:175], v[116:117], v[140:141] op_sel_hi:[1,0]
	v_pk_mul_f32 v[182:183], v[114:115], v[140:141] op_sel_hi:[1,0]
	v_pk_mul_f32 v[176:177], v[120:121], v[140:141] op_sel_hi:[1,0]
	v_pk_mul_f32 v[186:187], v[118:119], v[140:141] op_sel_hi:[1,0]
	global_load_dwordx4 v[118:121], v[158:159], off offset:192
	global_load_dwordx4 v[114:117], v[158:159], off offset:224
	v_lshl_add_u32 v230, v144, 7, v0
	v_lshl_add_u32 v231, v146, 7, v0
	v_lshl_add_u32 v232, v148, 7, v0
	v_lshl_add_u32 v234, v150, 7, v0
	v_lshl_add_u32 v235, v154, 7, v0
	v_lshlrev_b32_e32 v0, 4, v135
	v_and_b32_e32 v135, 0x70, v0
	v_mov_b32_e32 v0, v141
	v_pk_mul_f32 v[188:189], v[122:123], v[140:141] op_sel_hi:[1,0]
	v_pk_mul_f32 v[122:123], v[82:83], v[0:1] op_sel_hi:[1,0]
	v_mov_b32_e32 v247, v171
	v_mov_b32_e32 v246, v123
	v_pk_mul_f32 v[84:85], v[84:85], v[0:1] op_sel_hi:[1,0]
	v_mov_b32_e32 v244, v122
	v_mov_b32_e32 v245, v170
	v_pk_mul_f32 v[246:247], v[246:247], v[246:247]
	v_mov_b32_e32 v242, v84
	v_mov_b32_e32 v243, v164
	v_pk_fma_f32 v[244:245], v[244:245], v[244:245], v[246:247]
	v_pk_mul_f32 v[210:211], v[86:87], v[0:1] op_sel_hi:[1,0]
	v_mov_b32_e32 v248, v85
	v_mov_b32_e32 v249, v165
	v_pk_fma_f32 v[242:243], v[242:243], v[242:243], v[244:245]
	v_pk_mul_f32 v[124:125], v[124:125], v[140:141] op_sel_hi:[1,0]
	v_pk_fma_f32 v[242:243], v[248:249], v[248:249], v[242:243]
	v_mov_b32_e32 v140, v210
	v_mov_b32_e32 v141, v208
	v_pk_mul_f32 v[88:89], v[88:89], v[0:1] op_sel_hi:[1,0]
	v_mov_b32_e32 v178, v211
	v_mov_b32_e32 v179, v209
	v_pk_fma_f32 v[140:141], v[140:141], v[140:141], v[242:243]
	v_mov_b32_e32 v244, v88
	v_mov_b32_e32 v245, v166
	v_pk_fma_f32 v[140:141], v[178:179], v[178:179], v[140:141]
	v_pk_mul_f32 v[86:87], v[92:93], v[0:1] op_sel_hi:[1,0]
	v_pk_mul_f32 v[92:93], v[90:91], v[0:1] op_sel_hi:[1,0]
	v_mov_b32_e32 v248, v89
	v_mov_b32_e32 v249, v167
	v_pk_fma_f32 v[140:141], v[244:245], v[244:245], v[140:141]
	v_mov_b32_e32 v244, v92
	v_pk_fma_f32 v[140:141], v[248:249], v[248:249], v[140:141]
	v_mov_b32_e32 v245, v180
	v_mov_b32_e32 v248, v93
	v_mov_b32_e32 v249, v181
	v_pk_fma_f32 v[140:141], v[244:245], v[244:245], v[140:141]
	v_mov_b32_e32 v178, v86
	v_mov_b32_e32 v179, v168
	v_pk_fma_f32 v[140:141], v[248:249], v[248:249], v[140:141]
	v_pk_mul_f32 v[90:91], v[94:95], v[0:1] op_sel_hi:[1,0]
	v_mov_b32_e32 v242, v87
	v_mov_b32_e32 v243, v169
	v_pk_fma_f32 v[140:141], v[178:179], v[178:179], v[140:141]
	v_mov_b32_e32 v178, v90
	v_pk_fma_f32 v[140:141], v[242:243], v[242:243], v[140:141]
	v_mov_b32_e32 v179, v184
	v_pk_mul_f32 v[82:83], v[96:97], v[0:1] op_sel_hi:[1,0]
	v_mov_b32_e32 v246, v91
	v_mov_b32_e32 v247, v185
	v_pk_fma_f32 v[140:141], v[178:179], v[178:179], v[140:141]
	v_mov_b32_e32 v242, v82
	v_mov_b32_e32 v243, v172
	v_pk_fma_f32 v[140:141], v[246:247], v[246:247], v[140:141]
	v_pk_mul_f32 v[94:95], v[66:67], v[0:1] op_sel_hi:[1,0]
	v_mov_b32_e32 v244, v83
	v_mov_b32_e32 v245, v173
	v_pk_fma_f32 v[140:141], v[242:243], v[242:243], v[140:141]
	v_pk_mul_f32 v[68:69], v[68:69], v[0:1] op_sel_hi:[1,0]
	v_pk_fma_f32 v[140:141], v[244:245], v[244:245], v[140:141]
	v_mov_b32_e32 v244, v94
	v_mov_b32_e32 v245, v182
	v_pk_fma_f32 v[140:141], v[244:245], v[244:245], v[140:141]
	v_mov_b32_e32 v244, v95
	v_mov_b32_e32 v245, v183
	v_mov_b32_e32 v242, v68
	v_mov_b32_e32 v243, v174
	v_pk_fma_f32 v[140:141], v[244:245], v[244:245], v[140:141]
	v_pk_mul_f32 v[66:67], v[72:73], v[0:1] op_sel_hi:[1,0]
	v_pk_mul_f32 v[72:73], v[70:71], v[0:1] op_sel_hi:[1,0]
	v_mov_b32_e32 v244, v69
	v_mov_b32_e32 v245, v175
	v_pk_fma_f32 v[140:141], v[242:243], v[242:243], v[140:141]
	v_mov_b32_e32 v242, v72
	v_pk_fma_f32 v[140:141], v[244:245], v[244:245], v[140:141]
	v_mov_b32_e32 v243, v186
	v_pk_mul_f32 v[196:197], v[176:177], v[176:177]
	v_pk_mul_f32 v[178:179], v[66:67], v[66:67]
	v_mov_b32_e32 v244, v73
	v_mov_b32_e32 v245, v187
	v_pk_fma_f32 v[140:141], v[242:243], v[242:243], v[140:141]
	v_mov_b32_e32 v242, v178
	v_pk_fma_f32 v[140:141], v[244:245], v[244:245], v[140:141]
	v_mov_b32_e32 v243, v196
	v_pk_mul_f32 v[74:75], v[74:75], v[0:1] op_sel_hi:[1,0]
	v_pk_add_f32 v[140:141], v[242:243], v[140:141]
	v_mov_b32_e32 v196, v179
	v_pk_mul_f32 v[240:241], v[188:189], v[188:189]
	v_pk_add_f32 v[140:141], v[196:197], v[140:141]
	v_pk_mul_f32 v[196:197], v[74:75], v[74:75]
	v_pk_mul_f32 v[76:77], v[76:77], v[0:1] op_sel_hi:[1,0]
	v_mov_b32_e32 v242, v196
	v_mov_b32_e32 v243, v240
	v_pk_mul_f32 v[194:195], v[124:125], v[124:125]
	v_pk_mul_f32 v[178:179], v[76:77], v[76:77]
	v_pk_add_f32 v[140:141], v[242:243], v[140:141]
	v_mov_b32_e32 v240, v197
	v_pk_mul_f32 v[78:79], v[78:79], v[0:1] op_sel_hi:[1,0]
	v_pk_add_f32 v[140:141], v[240:241], v[140:141]
	v_mov_b32_e32 v196, v178
	v_mov_b32_e32 v197, v194
	v_pk_mul_f32 v[192:193], v[160:161], v[160:161]
	v_pk_mul_f32 v[96:97], v[78:79], v[78:79]
	v_pk_add_f32 v[140:141], v[196:197], v[140:141]
	v_mov_b32_e32 v194, v179
	v_pk_mul_f32 v[80:81], v[80:81], v[0:1] op_sel_hi:[1,0]
	v_pk_add_f32 v[140:141], v[194:195], v[140:141]
	v_mov_b32_e32 v178, v96
	v_mov_b32_e32 v179, v192
	v_pk_mul_f32 v[190:191], v[162:163], v[162:163]
	v_pk_mul_f32 v[70:71], v[80:81], v[80:81]
	v_pk_add_f32 v[140:141], v[178:179], v[140:141]
	v_mov_b32_e32 v192, v97
	v_pk_add_f32 v[96:97], v[192:193], v[140:141]
	v_mov_b32_e32 v140, v70
	v_mov_b32_e32 v141, v190
	v_pk_add_f32 v[96:97], v[140:141], v[96:97]
	v_mov_b32_e32 v190, v71
	v_pk_add_f32 v[70:71], v[190:191], v[96:97]
	ds_bpermute_b32 v97, v239, v71
	ds_bpermute_b32 v96, v239, v70
	s_mov_b32 s0, 0x358637bd
	s_mov_b32 s2, 0x3c800000
	v_add_u32_e32 v238, v215, v135
	v_xad_u32 v196, v135, 16, v215
	s_waitcnt lgkmcnt(0)
	v_pk_add_f32 v[96:97], v[70:71], v[96:97]
	v_mov_b64_e32 v[70:71], s[0:1]
	v_pk_fma_f32 v[96:97], v[96:97], s[2:3], v[70:71] op_sel_hi:[1,0,0]
	v_xad_u32 v195, v135, 32, v215
	v_mul_f32_e32 v0, 0x4b800000, v97
	v_cmp_gt_f32_e32 vcc, s58, v97
	v_xad_u32 v194, v135, 48, v215
	v_xad_u32 v192, v135, 64, v215
	v_cndmask_b32_e32 v0, v97, v0, vcc
	v_rsq_f32_e32 v0, v0
	v_xad_u32 v193, v135, s70, v215
	v_xad_u32 v191, v135, s63, v215
	v_xad_u32 v190, v135, s55, v215
	v_mul_f32_e32 v97, 0x45800000, v0
	v_cndmask_b32_e32 v0, v0, v97, vcc
	v_mul_f32_e32 v0, v237, v0
	v_pk_mul_f32 v[140:141], v[170:171], v[0:1] op_sel_hi:[1,0]
	v_pk_mul_f32 v[164:165], v[164:165], v[0:1] op_sel_hi:[1,0]
	s_waitcnt vmcnt(0)
	v_pk_mul_f32 v[140:141], v[126:127], v[140:141]
	v_pk_mul_f32 v[164:165], v[128:129], v[164:165]
	v_cvt_pk_bf16_f32 v140, v140, v141
	v_cvt_pk_bf16_f32 v141, v164, v165
	ds_write_b64 v238, v[140:141]
	v_pk_mul_f32 v[140:141], v[208:209], v[0:1] op_sel_hi:[1,0]
	v_pk_mul_f32 v[164:165], v[166:167], v[0:1] op_sel_hi:[1,0]
	v_pk_mul_f32 v[140:141], v[98:99], v[140:141]
	v_pk_mul_f32 v[164:165], v[100:101], v[164:165]
	v_cvt_pk_bf16_f32 v140, v140, v141
	v_cvt_pk_bf16_f32 v141, v164, v165
	ds_write_b64 v196, v[140:141]
	v_pk_mul_f32 v[140:141], v[180:181], v[0:1] op_sel_hi:[1,0]
	v_pk_mul_f32 v[164:165], v[168:169], v[0:1] op_sel_hi:[1,0]
	v_pk_mul_f32 v[140:141], v[130:131], v[140:141]
	v_pk_mul_f32 v[164:165], v[132:133], v[164:165]
	v_cvt_pk_bf16_f32 v140, v140, v141
	v_cvt_pk_bf16_f32 v141, v164, v165
	ds_write_b64 v195, v[140:141]
	v_pk_mul_f32 v[140:141], v[184:185], v[0:1] op_sel_hi:[1,0]
	v_pk_mul_f32 v[164:165], v[172:173], v[0:1] op_sel_hi:[1,0]
	v_pk_mul_f32 v[140:141], v[102:103], v[140:141]
	v_pk_mul_f32 v[164:165], v[104:105], v[164:165]
	v_cvt_pk_bf16_f32 v140, v140, v141
	v_cvt_pk_bf16_f32 v141, v164, v165
	ds_write_b64 v194, v[140:141]
	v_pk_mul_f32 v[140:141], v[182:183], v[0:1] op_sel_hi:[1,0]
	v_pk_mul_f32 v[164:165], v[174:175], v[0:1] op_sel_hi:[1,0]
	v_pk_mul_f32 v[140:141], v[110:111], v[140:141]
	v_pk_mul_f32 v[164:165], v[112:113], v[164:165]
	v_cvt_pk_bf16_f32 v140, v140, v141
	v_cvt_pk_bf16_f32 v141, v164, v165
	ds_write_b64 v192, v[140:141]
	v_pk_mul_f32 v[140:141], v[186:187], v[0:1] op_sel_hi:[1,0]
	v_pk_mul_f32 v[164:165], v[176:177], v[0:1] op_sel_hi:[1,0]
	v_pk_mul_f32 v[140:141], v[140:141], v[106:107]
	v_pk_mul_f32 v[164:165], v[164:165], v[108:109]
	v_cvt_pk_bf16_f32 v140, v140, v141
	v_cvt_pk_bf16_f32 v141, v164, v165
	ds_write_b64 v193, v[140:141]
	v_pk_mul_f32 v[140:141], v[188:189], v[0:1] op_sel_hi:[1,0]
	v_pk_mul_f32 v[124:125], v[124:125], v[0:1] op_sel_hi:[1,0]
	v_pk_mul_f32 v[140:141], v[140:141], v[118:119]
	v_pk_mul_f32 v[124:125], v[124:125], v[120:121]
	v_cvt_pk_bf16_f32 v140, v140, v141
	v_cvt_pk_bf16_f32 v141, v124, v125
	ds_write_b64 v191, v[140:141]
	v_pk_mul_f32 v[124:125], v[160:161], v[0:1] op_sel_hi:[1,0]
	v_pk_mul_f32 v[140:141], v[162:163], v[0:1] op_sel_hi:[1,0]
	v_mul_f32_e32 v0, 0x4b800000, v96
	v_cmp_gt_f32_e32 vcc, s58, v96
	v_pk_mul_f32 v[124:125], v[124:125], v[114:115]
	v_ashrrev_i32_e32 v135, 31, v134
	v_cndmask_b32_e32 v0, v96, v0, vcc
	v_rsq_f32_e32 v0, v0
	v_pk_mul_f32 v[96:97], v[140:141], v[116:117]
	v_cvt_pk_bf16_f32 v124, v124, v125
	v_cvt_pk_bf16_f32 v125, v96, v97
	v_mul_f32_e32 v96, 0x45800000, v0
	v_cndmask_b32_e32 v0, v0, v96, vcc
	v_mul_f32_e32 v0, v237, v0
	v_pk_mul_f32 v[96:97], v[122:123], v[0:1] op_sel_hi:[1,0]
	v_pk_mul_f32 v[84:85], v[84:85], v[0:1] op_sel_hi:[1,0]
	v_pk_mul_f32 v[96:97], v[126:127], v[96:97]
	v_pk_mul_f32 v[84:85], v[128:129], v[84:85]
	v_cvt_pk_bf16_f32 v96, v96, v97
	v_cvt_pk_bf16_f32 v97, v84, v85
	v_pk_mul_f32 v[84:85], v[210:211], v[0:1] op_sel_hi:[1,0]
	v_pk_mul_f32 v[88:89], v[88:89], v[0:1] op_sel_hi:[1,0]
	v_pk_mul_f32 v[84:85], v[98:99], v[84:85]
	v_pk_mul_f32 v[88:89], v[100:101], v[88:89]
	v_cvt_pk_bf16_f32 v84, v84, v85
	v_cvt_pk_bf16_f32 v85, v88, v89
	ds_write_b64 v238, v[96:97] offset:4096
	ds_write_b64 v196, v[84:85] offset:4096
	v_pk_mul_f32 v[84:85], v[92:93], v[0:1] op_sel_hi:[1,0]
	v_pk_mul_f32 v[86:87], v[86:87], v[0:1] op_sel_hi:[1,0]
	v_pk_mul_f32 v[84:85], v[130:131], v[84:85]
	v_pk_mul_f32 v[86:87], v[132:133], v[86:87]
	v_cvt_pk_bf16_f32 v84, v84, v85
	v_cvt_pk_bf16_f32 v85, v86, v87
	ds_write_b64 v195, v[84:85] offset:4096
	v_pk_mul_f32 v[84:85], v[90:91], v[0:1] op_sel_hi:[1,0]
	v_pk_mul_f32 v[82:83], v[82:83], v[0:1] op_sel_hi:[1,0]
	v_pk_mul_f32 v[84:85], v[102:103], v[84:85]
	v_pk_mul_f32 v[82:83], v[104:105], v[82:83]
	v_cvt_pk_bf16_f32 v84, v84, v85
	v_cvt_pk_bf16_f32 v85, v82, v83
	v_pk_mul_f32 v[82:83], v[94:95], v[0:1] op_sel_hi:[1,0]
	v_pk_mul_f32 v[68:69], v[68:69], v[0:1] op_sel_hi:[1,0]
	v_pk_mul_f32 v[82:83], v[110:111], v[82:83]
	v_pk_mul_f32 v[68:69], v[112:113], v[68:69]
	v_cvt_pk_bf16_f32 v82, v82, v83
	v_cvt_pk_bf16_f32 v83, v68, v69
	v_pk_mul_f32 v[68:69], v[72:73], v[0:1] op_sel_hi:[1,0]
	v_pk_mul_f32 v[66:67], v[66:67], v[0:1] op_sel_hi:[1,0]
	v_pk_mul_f32 v[68:69], v[106:107], v[68:69]
	v_pk_mul_f32 v[66:67], v[108:109], v[66:67]
	v_cvt_pk_bf16_f32 v68, v68, v69
	v_cvt_pk_bf16_f32 v69, v66, v67
	ds_write_b64 v194, v[84:85] offset:4096
	ds_write_b64 v192, v[82:83] offset:4096
	ds_write_b64 v193, v[68:69] offset:4096
	v_pk_mul_f32 v[66:67], v[74:75], v[0:1] op_sel_hi:[1,0]
	v_pk_mul_f32 v[68:69], v[76:77], v[0:1] op_sel_hi:[1,0]
	v_pk_mul_f32 v[66:67], v[118:119], v[66:67]
	v_pk_mul_f32 v[68:69], v[120:121], v[68:69]
	v_cvt_pk_bf16_f32 v66, v66, v67
	v_cvt_pk_bf16_f32 v67, v68, v69
	ds_write_b64 v191, v[66:67] offset:4096
	v_pk_mul_f32 v[66:67], v[78:79], v[0:1] op_sel_hi:[1,0]
	v_pk_mul_f32 v[68:69], v[80:81], v[0:1] op_sel_hi:[1,0]
	v_pk_mul_f32 v[66:67], v[114:115], v[66:67]
	v_pk_mul_f32 v[68:69], v[116:117], v[68:69]
	v_cvt_pk_bf16_f32 v66, v66, v67
	v_cvt_pk_bf16_f32 v67, v68, v69
	v_readlane_b32 s0, v250, 48
	v_ashrrev_i32_e32 v139, 31, v138
	ds_write_b64 v190, v[66:67] offset:4096
	v_lshlrev_b64 v[66:67], 12, v[134:135]
	v_readlane_b32 s1, v250, 49
	ds_write_b64 v190, v[124:125]
	v_lshlrev_b64 v[72:73], 1, v[138:139]
	v_lshl_add_u64 v[66:67], s[0:1], 0, v[66:67]
	v_lshl_add_u64 v[74:75], v[66:67], 0, v[72:73]
	ds_read_b128 v[66:69], v229
	v_lshlrev_b32_e32 v0, 4, v228
	v_and_b32_e32 v0, 0x70, v0
	v_lshl_add_u64 v[82:83], v[74:75], 0, v[0:1]
	ds_read_b128 v[74:77], v230
	v_lshl_add_u64 v[78:79], v[82:83], 0, v[142:143]
	s_waitcnt lgkmcnt(1)
	global_store_dwordx4 v[78:79], v[66:69], off nt
	ds_read_b128 v[66:69], v231
	v_ashrrev_i32_e32 v145, 31, v144
	v_lshlrev_b64 v[144:145], 12, v[144:145]
	v_ashrrev_i32_e32 v147, 31, v146
	v_lshlrev_b64 v[146:147], 12, v[146:147]
	v_lshl_add_u64 v[78:79], v[82:83], 0, v[144:145]
	s_waitcnt lgkmcnt(1)
	global_store_dwordx4 v[78:79], v[74:77], off nt
	ds_read_b128 v[74:77], v232
	v_lshl_add_u64 v[78:79], v[82:83], 0, v[146:147]
	s_waitcnt lgkmcnt(1)
	global_store_dwordx4 v[78:79], v[66:69], off nt
	ds_read_b128 v[66:69], v233
	v_ashrrev_i32_e32 v149, 31, v148
	v_lshlrev_b64 v[148:149], 12, v[148:149]
	v_lshl_add_u64 v[78:79], v[82:83], 0, v[148:149]
	s_waitcnt lgkmcnt(1)
	global_store_dwordx4 v[78:79], v[74:77], off nt
	v_lshl_add_u64 v[78:79], v[82:83], 0, v[152:153]
	ds_read_b128 v[74:77], v234
	s_waitcnt lgkmcnt(1)
	global_store_dwordx4 v[78:79], v[66:69], off nt
	ds_read_b128 v[66:69], v235
	ds_read_b128 v[78:81], v236
	v_ashrrev_i32_e32 v151, 31, v150
	v_lshlrev_b64 v[150:151], 12, v[150:151]
	v_ashrrev_i32_e32 v155, 31, v154
	v_lshlrev_b64 v[154:155], 12, v[154:155]
	v_lshl_add_u64 v[84:85], v[82:83], 0, v[150:151]
	s_waitcnt lgkmcnt(2)
	global_store_dwordx4 v[84:85], v[74:77], off nt
	v_pk_mul_f32 v[84:85], v[36:37], v[136:137] op_sel_hi:[1,0]
	v_pk_mul_f32 v[90:91], v[34:35], v[136:137] op_sel_hi:[1,0]
	v_lshl_add_u64 v[74:75], v[82:83], 0, v[154:155]
	s_waitcnt lgkmcnt(1)
	global_store_dwordx4 v[74:75], v[66:69], off nt
	v_pk_mul_f32 v[74:75], v[62:63], v[136:137] op_sel_hi:[1,0]
	v_pk_mul_f32 v[76:77], v[64:65], v[136:137] op_sel_hi:[1,0]
	v_lshl_add_u64 v[66:67], v[82:83], 0, v[156:157]
	s_waitcnt lgkmcnt(0)
	global_store_dwordx4 v[66:67], v[78:81], off nt
	global_load_dwordx4 v[62:65], v[158:159], off
	global_load_dwordx4 v[34:37], v[158:159], off offset:32
	v_pk_mul_f32 v[80:81], v[44:45], v[136:137] op_sel_hi:[1,0]
	v_pk_mul_f32 v[96:97], v[42:43], v[136:137] op_sel_hi:[1,0]
	global_load_dwordx4 v[66:69], v[158:159], off offset:64
	global_load_dwordx4 v[42:45], v[158:159], off offset:96
	v_pk_mul_f32 v[78:79], v[40:41], v[136:137] op_sel_hi:[1,0]
	v_pk_mul_f32 v[94:95], v[38:39], v[136:137] op_sel_hi:[1,0]
	v_pk_mul_f32 v[88:89], v[52:53], v[136:137] op_sel_hi:[1,0]
	v_pk_mul_f32 v[92:93], v[50:51], v[136:137] op_sel_hi:[1,0]
	global_load_dwordx4 v[50:53], v[158:159], off offset:128
	global_load_dwordx4 v[38:41], v[158:159], off offset:160
	v_pk_mul_f32 v[86:87], v[48:49], v[136:137] op_sel_hi:[1,0]
	v_pk_mul_f32 v[98:99], v[46:47], v[136:137] op_sel_hi:[1,0]
	v_pk_mul_f32 v[82:83], v[56:57], v[136:137] op_sel_hi:[1,0]
	v_pk_mul_f32 v[100:101], v[54:55], v[136:137] op_sel_hi:[1,0]
	global_load_dwordx4 v[54:57], v[158:159], off offset:192
	global_load_dwordx4 v[46:49], v[158:159], off offset:224
	v_mov_b32_e32 v116, v137
	v_pk_mul_f32 v[104:105], v[58:59], v[136:137] op_sel_hi:[1,0]
	v_pk_mul_f32 v[58:59], v[18:19], v[116:117] op_sel_hi:[1,0]
	v_mov_b32_e32 v103, v91
	v_mov_b32_e32 v102, v59
	v_pk_mul_f32 v[20:21], v[20:21], v[116:117] op_sel_hi:[1,0]
	v_mov_b32_e32 v18, v58
	v_mov_b32_e32 v19, v90
	v_pk_mul_f32 v[102:103], v[102:103], v[102:103]
	v_mov_b32_e32 v122, v20
	v_mov_b32_e32 v123, v84
	v_pk_fma_f32 v[124:125], v[18:19], v[18:19], v[102:103]
	v_pk_mul_f32 v[102:103], v[22:23], v[116:117] op_sel_hi:[1,0]
	v_pk_mul_f32 v[18:19], v[32:33], v[116:117] op_sel_hi:[1,0]
	v_mov_b32_e32 v32, v21
	v_mov_b32_e32 v33, v85
	v_pk_fma_f32 v[122:123], v[122:123], v[122:123], v[124:125]
	v_mov_b32_e32 v126, v102
	v_pk_fma_f32 v[32:33], v[32:33], v[32:33], v[122:123]
	v_mov_b32_e32 v127, v94
	v_pk_mul_f32 v[24:25], v[24:25], v[116:117] op_sel_hi:[1,0]
	v_mov_b32_e32 v128, v103
	v_mov_b32_e32 v129, v95
	v_pk_fma_f32 v[32:33], v[126:127], v[126:127], v[32:33]
	v_mov_b32_e32 v122, v24
	v_mov_b32_e32 v123, v78
	v_pk_fma_f32 v[32:33], v[128:129], v[128:129], v[32:33]
	v_pk_mul_f32 v[22:23], v[28:29], v[116:117] op_sel_hi:[1,0]
	v_pk_mul_f32 v[28:29], v[26:27], v[116:117] op_sel_hi:[1,0]
	v_mov_b32_e32 v124, v25
	v_mov_b32_e32 v125, v79
	v_pk_fma_f32 v[32:33], v[122:123], v[122:123], v[32:33]
	v_mov_b32_e32 v126, v28
	v_pk_fma_f32 v[32:33], v[124:125], v[124:125], v[32:33]
	v_mov_b32_e32 v127, v96
	v_mov_b32_e32 v128, v29
	v_mov_b32_e32 v129, v97
	v_pk_fma_f32 v[32:33], v[126:127], v[126:127], v[32:33]
	v_mov_b32_e32 v122, v22
	v_mov_b32_e32 v123, v80
	v_pk_fma_f32 v[32:33], v[128:129], v[128:129], v[32:33]
	v_pk_mul_f32 v[26:27], v[30:31], v[116:117] op_sel_hi:[1,0]
	v_mov_b32_e32 v124, v23
	v_mov_b32_e32 v125, v81
	v_pk_fma_f32 v[32:33], v[122:123], v[122:123], v[32:33]
	v_mov_b32_e32 v122, v26
	v_pk_fma_f32 v[32:33], v[124:125], v[124:125], v[32:33]
	v_mov_b32_e32 v123, v98
	v_mov_b32_e32 v30, v27
	v_mov_b32_e32 v31, v99
	v_pk_fma_f32 v[32:33], v[122:123], v[122:123], v[32:33]
	v_mov_b32_e32 v124, v18
	v_mov_b32_e32 v125, v86
	v_pk_fma_f32 v[30:31], v[30:31], v[30:31], v[32:33]
	v_pk_mul_f32 v[2:3], v[2:3], v[116:117] op_sel_hi:[1,0]
	v_mov_b32_e32 v126, v19
	v_mov_b32_e32 v127, v87
	v_pk_fma_f32 v[30:31], v[124:125], v[124:125], v[30:31]
	v_pk_mul_f32 v[4:5], v[4:5], v[116:117] op_sel_hi:[1,0]
	v_pk_fma_f32 v[30:31], v[126:127], v[126:127], v[30:31]
	v_mov_b32_e32 v126, v2
	v_mov_b32_e32 v127, v92
	v_mov_b32_e32 v128, v3
	v_mov_b32_e32 v129, v93
	v_pk_fma_f32 v[30:31], v[126:127], v[126:127], v[30:31]
	v_mov_b32_e32 v32, v4
	v_mov_b32_e32 v33, v88
	v_pk_fma_f32 v[30:31], v[128:129], v[128:129], v[30:31]
	v_pk_mul_f32 v[6:7], v[6:7], v[116:117] op_sel_hi:[1,0]
	v_mov_b32_e32 v124, v5
	v_mov_b32_e32 v125, v89
	v_pk_fma_f32 v[30:31], v[32:33], v[32:33], v[30:31]
	v_pk_mul_f32 v[8:9], v[8:9], v[116:117] op_sel_hi:[1,0]
	v_pk_fma_f32 v[30:31], v[124:125], v[124:125], v[30:31]
	v_mov_b32_e32 v32, v6
	v_mov_b32_e32 v33, v100
	v_pk_mul_f32 v[110:111], v[82:83], v[82:83]
	v_pk_mul_f32 v[122:123], v[8:9], v[8:9]
	v_mov_b32_e32 v124, v7
	v_mov_b32_e32 v125, v101
	v_pk_fma_f32 v[30:31], v[32:33], v[32:33], v[30:31]
	v_mov_b32_e32 v32, v122
	v_pk_fma_f32 v[30:31], v[124:125], v[124:125], v[30:31]
	v_mov_b32_e32 v33, v110
	v_pk_add_f32 v[30:31], v[32:33], v[30:31]
	v_mov_b32_e32 v110, v123
	v_pk_mul_f32 v[10:11], v[10:11], v[116:117] op_sel_hi:[1,0]
	v_pk_mul_f32 v[114:115], v[104:105], v[104:105]
	v_pk_add_f32 v[30:31], v[110:111], v[30:31]
	v_pk_mul_f32 v[110:111], v[10:11], v[10:11]
	v_pk_mul_f32 v[60:61], v[60:61], v[136:137] op_sel_hi:[1,0]
	v_pk_mul_f32 v[14:15], v[14:15], v[116:117] op_sel_hi:[1,0]
	v_pk_mul_f32 v[16:17], v[16:17], v[116:117] op_sel_hi:[1,0]
	v_pk_mul_f32 v[12:13], v[12:13], v[116:117] op_sel_hi:[1,0]
	v_mov_b32_e32 v116, v110
	v_mov_b32_e32 v117, v114
	v_pk_mul_f32 v[112:113], v[60:61], v[60:61]
	v_pk_mul_f32 v[32:33], v[12:13], v[12:13]
	v_pk_add_f32 v[30:31], v[116:117], v[30:31]
	v_mov_b32_e32 v114, v111
	v_pk_add_f32 v[30:31], v[114:115], v[30:31]
	v_mov_b32_e32 v110, v32
	v_mov_b32_e32 v111, v112
	v_pk_mul_f32 v[106:107], v[74:75], v[74:75]
	v_pk_mul_f32 v[118:119], v[14:15], v[14:15]
	v_pk_add_f32 v[30:31], v[110:111], v[30:31]
	v_mov_b32_e32 v112, v33
	v_pk_add_f32 v[30:31], v[112:113], v[30:31]
	v_mov_b32_e32 v32, v118
	v_mov_b32_e32 v33, v106
	v_pk_mul_f32 v[108:109], v[76:77], v[76:77]
	v_pk_mul_f32 v[120:121], v[16:17], v[16:17]
	v_pk_add_f32 v[30:31], v[32:33], v[30:31]
	v_mov_b32_e32 v106, v119
	v_pk_add_f32 v[30:31], v[106:107], v[30:31]
	v_mov_b32_e32 v32, v120
	v_mov_b32_e32 v33, v108
	v_pk_add_f32 v[30:31], v[32:33], v[30:31]
	v_mov_b32_e32 v108, v121
	v_pk_add_f32 v[30:31], v[108:109], v[30:31]
	ds_bpermute_b32 v33, v239, v31
	ds_bpermute_b32 v32, v239, v30
	v_readlane_b32 s37, v250, 20
	v_readlane_b32 s38, v250, 21
	v_readlane_b32 s39, v250, 22
	v_readlane_b32 s40, v250, 23
	s_waitcnt lgkmcnt(0)
	v_pk_add_f32 v[30:31], v[30:31], v[32:33]
	v_readlane_b32 s41, v250, 24
	v_pk_fma_f32 v[30:31], v[30:31], s[2:3], v[70:71] op_sel_hi:[1,0,0]
	v_readlane_b32 s42, v250, 25
	v_mul_f32_e32 v32, 0x4b800000, v31
	v_cmp_gt_f32_e32 vcc, s58, v31
	v_readlane_b32 s43, v250, 26
	s_mov_b64 s[12:13], s[48:49]
	v_cndmask_b32_e32 v31, v31, v32, vcc
	v_rsq_f32_e32 v31, v31
	s_mov_b64 s[14:15], s[50:51]
	v_mul_f32_e32 v32, 0x45800000, v31
	v_cndmask_b32_e32 v31, v31, v32, vcc
	v_mul_f32_e32 v32, v237, v31
	v_pk_mul_f32 v[70:71], v[90:91], v[32:33] op_sel_hi:[1,0]
	v_pk_mul_f32 v[84:85], v[84:85], v[32:33] op_sel_hi:[1,0]
	s_waitcnt vmcnt(7)
	v_pk_mul_f32 v[70:71], v[62:63], v[70:71]
	v_pk_mul_f32 v[84:85], v[64:65], v[84:85]
	v_cvt_pk_bf16_f32 v70, v70, v71
	v_cvt_pk_bf16_f32 v71, v84, v85
	ds_write_b64 v238, v[70:71]
	v_pk_mul_f32 v[70:71], v[94:95], v[32:33] op_sel_hi:[1,0]
	v_pk_mul_f32 v[78:79], v[78:79], v[32:33] op_sel_hi:[1,0]
	s_waitcnt vmcnt(6)
	v_pk_mul_f32 v[70:71], v[34:35], v[70:71]
	v_pk_mul_f32 v[78:79], v[36:37], v[78:79]
	v_cvt_pk_bf16_f32 v70, v70, v71
	v_cvt_pk_bf16_f32 v71, v78, v79
	ds_write_b64 v196, v[70:71]
	v_pk_mul_f32 v[70:71], v[96:97], v[32:33] op_sel_hi:[1,0]
	v_pk_mul_f32 v[78:79], v[80:81], v[32:33] op_sel_hi:[1,0]
	s_waitcnt vmcnt(5)
	v_pk_mul_f32 v[70:71], v[66:67], v[70:71]
	v_pk_mul_f32 v[78:79], v[68:69], v[78:79]
	v_cvt_pk_bf16_f32 v70, v70, v71
	v_cvt_pk_bf16_f32 v71, v78, v79
	ds_write_b64 v195, v[70:71]
	v_pk_mul_f32 v[70:71], v[98:99], v[32:33] op_sel_hi:[1,0]
	v_pk_mul_f32 v[78:79], v[86:87], v[32:33] op_sel_hi:[1,0]
	s_waitcnt vmcnt(4)
	v_pk_mul_f32 v[70:71], v[42:43], v[70:71]
	v_pk_mul_f32 v[78:79], v[44:45], v[78:79]
	v_cvt_pk_bf16_f32 v70, v70, v71
	v_cvt_pk_bf16_f32 v71, v78, v79
	ds_write_b64 v194, v[70:71]
	v_pk_mul_f32 v[70:71], v[92:93], v[32:33] op_sel_hi:[1,0]
	v_pk_mul_f32 v[78:79], v[88:89], v[32:33] op_sel_hi:[1,0]
	s_waitcnt vmcnt(3)
	v_pk_mul_f32 v[70:71], v[50:51], v[70:71]
	v_pk_mul_f32 v[78:79], v[52:53], v[78:79]
	v_cvt_pk_bf16_f32 v70, v70, v71
	v_cvt_pk_bf16_f32 v71, v78, v79
	ds_write_b64 v192, v[70:71]
	v_pk_mul_f32 v[70:71], v[100:101], v[32:33] op_sel_hi:[1,0]
	v_pk_mul_f32 v[78:79], v[82:83], v[32:33] op_sel_hi:[1,0]
	s_waitcnt vmcnt(2)
	v_pk_mul_f32 v[70:71], v[70:71], v[38:39]
	v_pk_mul_f32 v[78:79], v[78:79], v[40:41]
	v_cvt_pk_bf16_f32 v70, v70, v71
	v_cvt_pk_bf16_f32 v71, v78, v79
	ds_write_b64 v193, v[70:71]
	v_pk_mul_f32 v[70:71], v[104:105], v[32:33] op_sel_hi:[1,0]
	v_pk_mul_f32 v[60:61], v[60:61], v[32:33] op_sel_hi:[1,0]
	s_waitcnt vmcnt(1)
	v_pk_mul_f32 v[70:71], v[70:71], v[54:55]
	v_pk_mul_f32 v[60:61], v[60:61], v[56:57]
	v_mul_f32_e32 v31, 0x4b800000, v30
	v_cmp_gt_f32_e32 vcc, s58, v30
	v_cvt_pk_bf16_f32 v70, v70, v71
	v_cvt_pk_bf16_f32 v71, v60, v61
	v_cndmask_b32_e32 v30, v30, v31, vcc
	ds_write_b64 v191, v[70:71]
	v_rsq_f32_e32 v70, v30
	v_pk_mul_f32 v[60:61], v[74:75], v[32:33] op_sel_hi:[1,0]
	v_pk_mul_f32 v[32:33], v[76:77], v[32:33] op_sel_hi:[1,0]
	s_waitcnt vmcnt(0)
	v_pk_mul_f32 v[60:61], v[60:61], v[46:47]
	v_pk_mul_f32 v[30:31], v[32:33], v[48:49]
	v_cvt_pk_bf16_f32 v60, v60, v61
	v_cvt_pk_bf16_f32 v61, v30, v31
	v_mul_f32_e32 v30, 0x45800000, v70
	v_cndmask_b32_e32 v30, v70, v30, vcc
	v_mul_f32_e32 v30, v237, v30
	v_pk_mul_f32 v[32:33], v[58:59], v[30:31] op_sel_hi:[1,0]
	v_pk_mul_f32 v[20:21], v[20:21], v[30:31] op_sel_hi:[1,0]
	v_pk_mul_f32 v[32:33], v[62:63], v[32:33]
	v_pk_mul_f32 v[20:21], v[64:65], v[20:21]
	v_cvt_pk_bf16_f32 v32, v32, v33
	v_cvt_pk_bf16_f32 v33, v20, v21
	v_pk_mul_f32 v[20:21], v[102:103], v[30:31] op_sel_hi:[1,0]
	v_pk_mul_f32 v[24:25], v[24:25], v[30:31] op_sel_hi:[1,0]
	v_pk_mul_f32 v[20:21], v[34:35], v[20:21]
	v_pk_mul_f32 v[24:25], v[36:37], v[24:25]
	v_cvt_pk_bf16_f32 v20, v20, v21
	v_cvt_pk_bf16_f32 v21, v24, v25
	ds_write_b64 v238, v[32:33] offset:4096
	ds_write_b64 v196, v[20:21] offset:4096
	v_pk_mul_f32 v[20:21], v[28:29], v[30:31] op_sel_hi:[1,0]
	v_pk_mul_f32 v[22:23], v[22:23], v[30:31] op_sel_hi:[1,0]
	v_pk_mul_f32 v[20:21], v[66:67], v[20:21]
	v_pk_mul_f32 v[22:23], v[68:69], v[22:23]
	v_cvt_pk_bf16_f32 v20, v20, v21
	v_cvt_pk_bf16_f32 v21, v22, v23
	ds_write_b64 v195, v[20:21] offset:4096
	v_pk_mul_f32 v[20:21], v[26:27], v[30:31] op_sel_hi:[1,0]
	v_pk_mul_f32 v[18:19], v[18:19], v[30:31] op_sel_hi:[1,0]
	v_pk_mul_f32 v[2:3], v[2:3], v[30:31] op_sel_hi:[1,0]
	v_pk_mul_f32 v[4:5], v[4:5], v[30:31] op_sel_hi:[1,0]
	v_pk_mul_f32 v[20:21], v[42:43], v[20:21]
	v_pk_mul_f32 v[18:19], v[44:45], v[18:19]
	v_pk_mul_f32 v[2:3], v[50:51], v[2:3]
	v_pk_mul_f32 v[4:5], v[52:53], v[4:5]
	v_cvt_pk_bf16_f32 v20, v20, v21
	v_cvt_pk_bf16_f32 v21, v18, v19
	v_cvt_pk_bf16_f32 v2, v2, v3
	v_cvt_pk_bf16_f32 v3, v4, v5
	ds_write_b64 v194, v[20:21] offset:4096
	ds_write_b64 v192, v[2:3] offset:4096
	v_pk_mul_f32 v[2:3], v[6:7], v[30:31] op_sel_hi:[1,0]
	v_pk_mul_f32 v[4:5], v[8:9], v[30:31] op_sel_hi:[1,0]
	v_pk_mul_f32 v[2:3], v[38:39], v[2:3]
	v_pk_mul_f32 v[4:5], v[40:41], v[4:5]
	v_cvt_pk_bf16_f32 v2, v2, v3
	v_cvt_pk_bf16_f32 v3, v4, v5
	ds_write_b64 v193, v[2:3] offset:4096
	v_pk_mul_f32 v[2:3], v[10:11], v[30:31] op_sel_hi:[1,0]
	v_pk_mul_f32 v[4:5], v[12:13], v[30:31] op_sel_hi:[1,0]
	v_pk_mul_f32 v[2:3], v[54:55], v[2:3]
	v_pk_mul_f32 v[4:5], v[56:57], v[4:5]
	v_cvt_pk_bf16_f32 v2, v2, v3
	v_cvt_pk_bf16_f32 v3, v4, v5
	ds_write_b64 v191, v[2:3] offset:4096
	v_pk_mul_f32 v[2:3], v[14:15], v[30:31] op_sel_hi:[1,0]
	v_pk_mul_f32 v[4:5], v[16:17], v[30:31] op_sel_hi:[1,0]
	v_pk_mul_f32 v[2:3], v[46:47], v[2:3]
	v_pk_mul_f32 v[4:5], v[48:49], v[4:5]
	v_cvt_pk_bf16_f32 v2, v2, v3
	v_cvt_pk_bf16_f32 v3, v4, v5
	ds_write_b64 v190, v[2:3] offset:4096
	v_or_b32_e32 v2, 64, v134
	v_ashrrev_i32_e32 v3, 31, v2
	ds_write_b64 v190, v[60:61]
	v_lshlrev_b64 v[2:3], 12, v[2:3]
	v_lshl_add_u64 v[6:7], s[0:1], 0, v[2:3]
	ds_read_b128 v[2:5], v229
	v_lshl_add_u64 v[6:7], v[6:7], 0, v[72:73]
	v_lshl_add_u64 v[14:15], v[6:7], 0, v[0:1]
	ds_read_b128 v[6:9], v230
	v_lshl_add_u64 v[10:11], v[14:15], 0, v[142:143]
	s_waitcnt lgkmcnt(1)
	global_store_dwordx4 v[10:11], v[2:5], off nt
	ds_read_b128 v[2:5], v231
	v_lshl_add_u64 v[10:11], v[14:15], 0, v[144:145]
	s_waitcnt lgkmcnt(1)
	global_store_dwordx4 v[10:11], v[6:9], off nt
	ds_read_b128 v[6:9], v232
	v_lshl_add_u64 v[10:11], v[14:15], 0, v[146:147]
	s_waitcnt lgkmcnt(1)
	global_store_dwordx4 v[10:11], v[2:5], off nt
	ds_read_b128 v[2:5], v233
	v_lshl_add_u64 v[10:11], v[14:15], 0, v[148:149]
	s_waitcnt lgkmcnt(1)
	global_store_dwordx4 v[10:11], v[6:9], off nt
	v_lshl_add_u64 v[10:11], v[14:15], 0, v[152:153]
	ds_read_b128 v[6:9], v234
	s_waitcnt lgkmcnt(1)
	global_store_dwordx4 v[10:11], v[2:5], off nt
	ds_read_b128 v[2:5], v235
	ds_read_b128 v[10:13], v236
	v_lshl_add_u64 v[16:17], v[14:15], 0, v[150:151]
	s_waitcnt lgkmcnt(2)
	global_store_dwordx4 v[16:17], v[6:9], off nt
	s_nop 1
	v_lshl_add_u64 v[6:7], v[14:15], 0, v[154:155]
	s_waitcnt lgkmcnt(1)
	global_store_dwordx4 v[6:7], v[2:5], off nt
	s_nop 1
	v_lshl_add_u64 v[2:3], v[14:15], 0, v[156:157]
	s_waitcnt lgkmcnt(0)
	global_store_dwordx4 v[2:3], v[10:13], off nt
	s_branch .LBB0_1240
